# FoX attention: second barrier per K iteration, waves 4-7 run half an iteration behind waves 0-3 (MFMA half beside softmax half)
# speedup vs baseline: 1.0156x; 1.0156x over previous
.LBB0_171:
	s_and_b64 vcc, exec, s[30:31]
	s_cbranch_vccnz .Lfx_lead_out
	s_barrier

.LBB0_174:
	s_lshl_b32 s37, s71, 10
	s_add_i32 s39, s37, 0
	s_lshl_b32 s37, s38, 3
	s_add_i32 s37, s37, s71
	s_ashr_i32 s46, s37, 1
	s_lshl_b32 s37, s38, 2
	s_or_b32 s47, s37, 3
	s_lshl_b32 s78, s47, 6
	s_lshl_b64 s[48:49], s[78:79], s41
	s_add_i32 s37, s39, 0x14000
	v_lshl_add_u64 v[2:3], s[48:49], 1, v[180:181]
	s_mov_b32 s48, m0
	s_mov_b32 m0, s37
	s_nop 0
	global_load_lds_dwordx4 v[2:3], off
	s_mov_b32 m0, s48
	s_mov_b32 s37, s79
	v_lshl_add_u64 v[2:3], v[2:3], 0, s[36:37]
	s_add_i32 s48, s39, 0x16000
	s_mov_b32 s49, m0
	s_mov_b32 m0, s48
	s_nop 0
	global_load_lds_dwordx4 v[2:3], off
	s_mov_b32 m0, s49
	s_or_b32 s78, s44, 0x80
	s_lshl_b64 s[48:49], s[78:79], s41
	v_lshl_add_u64 v[2:3], s[48:49], 1, v[180:181]
	s_add_i32 s48, s39, 0x10000
	s_mov_b32 s49, m0
	s_mov_b32 m0, s48
	s_nop 0
	global_load_lds_dwordx4 v[2:3], off
	s_mov_b32 m0, s49
	v_lshl_add_u64 v[2:3], v[2:3], 0, s[36:37]
	s_add_i32 s48, s39, 0x12000
	s_mov_b32 s49, m0
	s_mov_b32 m0, s48
	s_nop 0
	global_load_lds_dwordx4 v[2:3], off
	s_mov_b32 m0, s49
	s_or_b32 s78, s44, 64
	s_lshl_b64 s[48:49], s[78:79], s41
	v_lshl_add_u64 v[2:3], s[48:49], 1, v[180:181]
	s_add_i32 s48, s39, 0xc000
	s_mov_b32 s49, m0
	s_mov_b32 m0, s48
	s_nop 0
	global_load_lds_dwordx4 v[2:3], off
	s_mov_b32 m0, s49
	v_lshl_add_u64 v[2:3], v[2:3], 0, s[36:37]
	v_mov_b32_e32 v14, v0
	v_mov_b32_e32 v15, v0
	s_add_i32 s45, s39, 0x8000
	s_add_i32 s39, s39, 0xe000
	s_mov_b32 s37, m0
	s_mov_b32 m0, s39
	s_nop 0
	global_load_lds_dwordx4 v[2:3], off
	s_mov_b32 m0, s37
	v_mov_b32_e32 v1, v0
	v_mov_b32_e32 v2, v0
	v_mov_b32_e32 v3, v0
	v_mov_b32_e32 v4, v0
	v_mov_b32_e32 v5, v0
	v_mov_b32_e32 v6, v0
	v_mov_b32_e32 v7, v0
	v_mov_b32_e32 v8, v0
	v_mov_b32_e32 v9, v0
	v_mov_b32_e32 v10, v0
	v_mov_b32_e32 v11, v0
	v_mov_b32_e32 v12, v0
	v_mov_b32_e32 v13, v0
	v_mov_b32_e32 v132, v0
	v_mov_b32_e32 v133, v0
	v_mov_b64_e32 v[32:33], v[14:15]
	s_lshl_b32 s37, s46, 14
	v_mov_b32_e32 v130, v0
	v_mov_b32_e32 v131, v0
	v_mov_b64_e32 v[136:137], v[132:133]
	v_mov_b64_e32 v[148:149], v[132:133]
	v_mov_b64_e32 v[152:153], v[132:133]
	v_mov_b64_e32 v[140:141], v[132:133]
	v_mov_b64_e32 v[144:145], v[132:133]
	v_mov_b64_e32 v[156:157], v[132:133]
	v_mov_b64_e32 v[160:161], v[132:133]
	v_mov_b64_e32 v[30:31], v[12:13]
	v_mov_b64_e32 v[28:29], v[10:11]
	v_mov_b64_e32 v[26:27], v[8:9]
	v_mov_b64_e32 v[24:25], v[6:7]
	v_mov_b64_e32 v[22:23], v[4:5]
	v_mov_b64_e32 v[20:21], v[2:3]
	v_mov_b64_e32 v[18:19], v[0:1]
	v_mov_b64_e32 v[16:17], v[14:15]
	s_and_b32 s48, s37, 0xc000
	v_lshl_add_u32 v175, s38, 10, v204
	s_lshl_b32 s49, s38, 16
	s_mov_b32 s50, 0
	v_mov_b32_e32 v207, 0xf149f2ca
	v_mov_b32_e32 v206, 0
	v_mov_b32_e32 v110, 0
	v_mov_b32_e32 v111, 0
	v_mov_b32_e32 v112, 0
	v_mov_b32_e32 v113, 0
	v_mov_b32_e32 v114, 0
	v_mov_b32_e32 v115, 0
	v_mov_b32_e32 v116, 0
	v_mov_b32_e32 v117, 0
	v_mov_b32_e32 v118, 0
	v_mov_b32_e32 v119, 0
	v_mov_b32_e32 v120, 0
	v_mov_b32_e32 v121, 0
	v_mov_b32_e32 v122, 0
	v_mov_b32_e32 v123, 0
	v_mov_b32_e32 v124, 0
	v_mov_b32_e32 v125, 0
	v_mov_b64_e32 v[134:135], v[130:131]
	v_mov_b64_e32 v[146:147], v[130:131]
	v_mov_b64_e32 v[150:151], v[130:131]
	v_mov_b64_e32 v[138:139], v[130:131]
	v_mov_b64_e32 v[142:143], v[130:131]
	v_mov_b64_e32 v[154:155], v[130:131]
	v_mov_b64_e32 v[158:159], v[130:131]
	v_mov_b64_e32 v[14:15], v[12:13]
	v_mov_b64_e32 v[12:13], v[10:11]
	v_mov_b64_e32 v[10:11], v[8:9]
	v_mov_b64_e32 v[8:9], v[6:7]
	v_mov_b64_e32 v[6:7], v[4:5]
	v_mov_b64_e32 v[4:5], v[2:3]
	v_mov_b64_e32 v[2:3], v[0:1]
	s_waitcnt vmcnt(0)
	s_andn2_b64 vcc, exec, s[30:31]
	s_cbranch_vccnz .Lfx_lead_in
	s_barrier
.Lfx_lead_in:
	s_cmp_lt_u32 s47, 2
	s_mov_b64 s[38:39], -1
	s_cbranch_scc0 .LBB0_176

.LBB0_187:
	s_waitcnt lgkmcnt(0)
	s_barrier
	v_sub_f32_e32 v110, v49, v1
	v_sub_f32_e32 v111, v48, v1
	v_sub_f32_e32 v112, v47, v1
	v_sub_f32_e32 v113, v46, v1
	v_sub_f32_e32 v115, v45, v1
	v_sub_f32_e32 v116, v44, v1
	v_sub_f32_e32 v117, v43, v1
	v_sub_f32_e32 v118, v42, v1
	v_sub_f32_e32 v47, v41, v1
	v_sub_f32_e32 v46, v40, v1
	v_sub_f32_e32 v43, v39, v1
	v_sub_f32_e32 v42, v38, v1
	v_sub_f32_e32 v39, v37, v1
	v_sub_f32_e32 v38, v36, v1
	v_sub_f32_e32 v35, v35, v1
	v_sub_f32_e32 v34, v34, v1
	v_sub_f32_e32 v65, v65, v1
	v_sub_f32_e32 v64, v64, v1
	v_sub_f32_e32 v119, v63, v1
	v_sub_f32_e32 v62, v62, v1
	v_sub_f32_e32 v120, v61, v1
	v_sub_f32_e32 v60, v60, v1
	v_sub_f32_e32 v121, v59, v1
	v_sub_f32_e32 v58, v58, v1
	v_sub_f32_e32 v49, v57, v1
	v_sub_f32_e32 v48, v56, v1
	v_sub_f32_e32 v45, v55, v1
	v_sub_f32_e32 v44, v54, v1
	v_sub_f32_e32 v41, v53, v1
	v_sub_f32_e32 v40, v52, v1
	v_sub_f32_e32 v37, v51, v1
	v_sub_f32_e32 v36, v50, v1
	v_exp_f32_e32 v34, v34
	v_exp_f32_e32 v36, v36
	v_exp_f32_e32 v35, v35
	v_exp_f32_e32 v37, v37
	v_exp_f32_e32 v38, v38
	v_exp_f32_e32 v40, v40
	v_exp_f32_e32 v39, v39
	v_exp_f32_e32 v41, v41
	v_exp_f32_e32 v42, v42
	v_exp_f32_e32 v44, v44
	v_exp_f32_e32 v43, v43
	v_exp_f32_e32 v45, v45
	v_exp_f32_e32 v46, v46
	v_exp_f32_e32 v48, v48
	v_exp_f32_e32 v47, v47
	v_exp_f32_e32 v49, v49
	v_exp_f32_e32 v50, v118
	v_exp_f32_e32 v52, v58
	v_exp_f32_e32 v51, v117
	v_exp_f32_e32 v54, v116
	v_exp_f32_e32 v56, v60
	v_exp_f32_e32 v55, v115
	v_exp_f32_e32 v58, v113
	v_exp_f32_e32 v60, v62
	v_exp_f32_e32 v59, v112
	v_exp_f32_e32 v62, v111
	v_exp_f32_e32 v64, v64
	v_exp_f32_e32 v63, v110
	v_exp_f32_e32 v65, v65
	v_exp_f32_e32 v61, v119
	v_exp_f32_e32 v57, v120
	v_exp_f32_e32 v53, v121
	v_pk_add_f32 v[110:111], v[64:65], v[62:63]
	v_pk_add_f32 v[112:113], v[60:61], v[58:59]
	v_pk_add_f32 v[116:117], v[56:57], v[54:55]
	v_pk_add_f32 v[118:119], v[52:53], v[50:51]
	v_pk_add_f32 v[120:121], v[48:49], v[46:47]
	v_pk_add_f32 v[122:123], v[44:45], v[42:43]
	v_pk_add_f32 v[124:125], v[40:41], v[38:39]
	v_pk_add_f32 v[130:131], v[36:37], v[34:35]
	v_add_f32_e32 v124, v124, v125
	v_add_f32_e32 v115, v130, v131
	v_add_f32_e32 v122, v122, v123
	v_add_f32_e32 v120, v120, v121
	v_add_f32_e32 v118, v118, v119
	v_add_f32_e32 v116, v116, v117
	v_add_f32_e32 v112, v112, v113
	v_add_f32_e32 v110, v110, v111
	v_add_f32_e32 v115, v115, v124
	v_add_f32_e32 v120, v122, v120
	v_add_f32_e32 v116, v118, v116
	v_add_f32_e32 v110, v112, v110
	v_add_f32_e32 v111, v115, v120
	v_add_f32_e32 v110, v116, v110
	v_add_f32_e32 v130, v111, v110
	v_fmac_f32_e32 v130, v206, v114
	v_cvt_pk_bf16_f32 v122, v34, v35
	v_cvt_pk_bf16_f32 v123, v38, v39
	v_cvt_pk_bf16_f32 v124, v42, v43
	v_cvt_pk_bf16_f32 v125, v46, v47
	v_cvt_pk_bf16_f32 v118, v50, v51
	v_cvt_pk_bf16_f32 v119, v54, v55
	v_cvt_pk_bf16_f32 v120, v58, v59
	v_cvt_pk_bf16_f32 v121, v62, v63
	v_cvt_pk_bf16_f32 v114, v36, v37
	v_cvt_pk_bf16_f32 v115, v40, v41
	v_cvt_pk_bf16_f32 v116, v44, v45
	v_cvt_pk_bf16_f32 v117, v48, v49
	v_cvt_pk_bf16_f32 v110, v52, v53
	v_cvt_pk_bf16_f32 v111, v56, v57
	v_cvt_pk_bf16_f32 v112, v60, v61
	v_cvt_pk_bf16_f32 v113, v64, v65
	v_mov_b32_e32 v206, v130
	s_branch .LBB0_189
.LBB0_188:
	s_barrier
	v_mov_b64_e32 v[164:165], v[144:145]
	v_mov_b64_e32 v[162:163], v[142:143]
	v_mov_b64_e32 v[144:145], v[140:141]
	v_mov_b64_e32 v[142:143], v[138:139]
	v_mov_b64_e32 v[140:141], v[136:137]
	v_mov_b64_e32 v[138:139], v[134:135]
	v_mov_b64_e32 v[136:137], v[132:133]
	v_mov_b32_e32 v1, v207
	v_mov_b64_e32 v[134:135], v[130:131]
